# combo34 with the early L2 write-back issued by the 7/8-th arriver of each XCD instead of the 3/4-th
# speedup vs baseline: 1.0117x; 1.0091x over previous
; __device__ __forceinline__ unsigned xb_ld(unsigned* p)              { return __hip_atomic_load(p, __ATOMIC_RELAXED, __HIP_MEMORY_SCOPE_AGENT); }
; __device__ __forceinline__ unsigned xb_add(unsigned* p, unsigned v) { return __hip_atomic_fetch_add(p, v, __ATOMIC_RELAXED, __HIP_MEMORY_SCOPE_AGENT); }
; #define XB_SPIN(cond, bar) do { unsigned _sp = 0; while (cond) { __builtin_amdgcn_s_sleep(1); \
;     if ((++_sp & 255u) == 0u) { if (xb_ld(&(bar)[XB_TMO])) break; if (_sp > XB_SPIN_CAP) { atomicAdd(&(bar)[XB_TMO], 1u); break; } } } } while (0)
; __device__ __forceinline__ void xcd_barrier(const XcdBarrier& b, const bool xb_is_leader) {
;     ...
;         const unsigned old = xb_add(&bar[XB_XSUB(b.x)], 1u);
;         const unsigned gen = old / nloc;
;         if (old + 1u == (gen + 1u) * nloc) {
;             __builtin_amdgcn_fence(__ATOMIC_RELEASE, "agent");
;             asm volatile("s_waitcnt vmcnt(0)" ::: "memory");
;             const unsigned og = xb_add(&bar[XB_TOP], 1u);
;             const unsigned tg = og / nx;
;             if (og + 1u == (tg + 1u) * nx) xb_add(&bar[XB_TOPGEN], 1u);
;             else XB_SPIN(xb_ld(&bar[XB_TOPGEN]) == tg, bar);
.LBB0_204:
	s_or_b64 exec, exec, s[8:9]
	v_cvt_f32_u32_e32 v4, v2
	s_waitcnt vmcnt(0)
	v_readfirstlane_b32 s0, v3
	v_sub_u32_e32 v3, 0, v2
	v_rcp_iflag_f32_e32 v4, v4
	v_add_u32_e32 v5, s0, v1
	v_mul_f32_e32 v4, 0x4f7ffffe, v4
	v_cvt_u32_f32_e32 v4, v4
	v_mul_lo_u32 v1, v3, v4
	v_mul_hi_u32 v1, v4, v1
	v_add_u32_e32 v1, v4, v1
	v_mul_hi_u32 v1, v5, v1
	v_mul_lo_u32 v3, v1, v2
	v_sub_u32_e32 v3, v5, v3
	v_add_u32_e32 v4, 1, v1
	v_cmp_ge_u32_e32 vcc, v3, v2
	s_nop 1
	v_cndmask_b32_e32 v1, v1, v4, vcc
	v_sub_u32_e32 v4, v3, v2
	v_cndmask_b32_e32 v3, v3, v4, vcc
	v_add_u32_e32 v4, 1, v1
	v_cmp_ge_u32_e32 vcc, v3, v2
	v_add_u32_e32 v3, 1, v5
	s_nop 0
	v_cndmask_b32_e32 v1, v1, v4, vcc
	v_mul_lo_u32 v4, v2, v1
	v_add_u32_e32 v2, v4, v2
	v_cmp_ne_u32_e32 vcc, v3, v2
	s_and_saveexec_b64 s[0:1], vcc
	s_xor_b64 s[0:1], exec, s[0:1]
	s_cbranch_execz .LBB0_218
	s_waitcnt lgkmcnt(0)
	v_sub_u32_e32 v0, v2, v4
	v_lshrrev_b32_e32 v0, 3, v0
	v_sub_u32_e32 v0, v2, v0
	v_cmp_eq_u32_e32 vcc, v5, v0
	s_cbranch_vccz .Lxb_noflush_1
	buffer_wbl2 sc1
